# latent-mixer item prologue: second key tile's loads issued before waiting for the first tile (both in flight)
# baseline (speedup 1.0000x reference)
; #define WAIT_ALL(S) asm volatile("s_waitcnt vmcnt(0)" : "+v"(rk0##S), "+v"(rk1##S), "+v"(rv0##S), "+v"(rv1##S), "+v"(rkr##S), "+v"(rck##S))
; template <int TYPE>
; DI void attn_item(KargPtr p, int b, int h, int qb, unsigned char* smem) {
;     ...
;     const bf16_t* Kg = (TYPE == 0 ? p->kf : TYPE == 1 ? p->kn : p->ks) + (size_t)b * SEQ * 512 + h * 64;
;     const bf16_t* Vg = (TYPE == 0 ? p->vtf : TYPE == 1 ? p->vtm : p->vts) + (size_t)(b * 8 + h) * 64 * SEQ;
;     const bf16_t* Krg = p->kr + (size_t)b * SEQ * 32;
;     const float* cumg = p->cum + (size_t)(b * 8 + h) * SEQ;
;     const int ntiles = 2 * qb + 2;
;     u32x4 rk0A, rk1A, rv0A, rv1A, rkrA, rk0B, rk1B, rv0B, rv1B, rkrB; float rckA = 0.f, rckB = 0.f;
;     { unsigned z_ = 0u; asm volatile("" : "+v"(z_)); rkrA = (u32x4){z_, z_, z_, z_}; rkrB = rkrA; }
;     const int ldrow = tid >> 3, ldch = tid & 7;
;     const int vpos = 16 * (ldch >> 1) + 4 * (ldch & 1);
;     ...
;     __syncthreads();
;     if (TYPE != 1 && tid < 16) flags[tid] = 0;
;     LOAD_TILE(A, TILE_OF(0));
;     WAIT_ALL(A);
;     STORE_TILE(A, 0);
;     LOAD_TILE(A, TILE_OF(1));
;     __syncthreads();
.LBB0_587:
	s_and_b64 vcc, exec, s[4:5]
	s_cbranch_vccz .LBB0_565
	s_ashr_i32 s22, s26, 9
	s_mul_i32 s2, s22, 13
	s_bfe_u32 s4, s26, 0x20007
	s_add_i32 s2, s2, s26
	s_and_b32 s24, s2, 63
	s_and_b32 s5, s26, 0x200
	s_xor_b32 s6, s4, 3
	s_cmp_eq_u32 s5, 0
	s_cselect_b32 s23, s4, s6
	s_lshl_b32 s4, s22, 2
	s_or_b32 s4, s4, s23
	s_sub_i32 s13, 31, s4
	s_lshr_b32 s4, s26, 6
	s_add_i32 s4, s4, s22
	s_bitcmp1_b32 s4, 0
	s_cselect_b64 s[6:7], -1, 0
	s_mov_b64 s[4:5], -1
	s_and_b64 vcc, exec, s[6:7]
	s_cbranch_vccz .LBB0_596
	v_mov_b32_e32 v22, v199
	s_load_dwordx8 s[4:11], s[0:1], 0x120
	v_ashrrev_i32_e32 v0, 1, v22
	v_and_b32_e32 v0, 0xffffffe0, v0
	v_and_b32_e32 v33, 31, v22
	v_lshl_add_u32 v176, s13, 7, v0
	s_lshr_b32 s14, s24, 3
	v_or_b32_e32 v0, v176, v33
	s_lshl_b32 s84, s14, 12
	v_ashrrev_i32_e32 v1, 31, v0
	v_lshl_add_u64 v[4:5], v[0:1], 0, s[84:85]
	s_and_b32 s15, s2, 7
	v_lshlrev_b64 v[0:1], 10, v[4:5]
	v_bfe_u32 v133, v22, 5, 1
	s_waitcnt lgkmcnt(0)
	v_lshl_add_u64 v[0:1], s[6:7], 0, v[0:1]
	s_lshl_b32 s6, s15, 7
	s_mov_b32 s7, s85
	v_lshl_add_u64 v[0:1], v[0:1], 0, s[6:7]
	v_lshlrev_b32_e32 v2, 4, v133
	v_lshlrev_b64 v[4:5], 9, v[4:5]
	s_lshl_b32 s84, s15, 6
	v_lshl_add_u64 v[6:7], v[0:1], 0, v[2:3]
	v_lshl_add_u64 v[4:5], s[8:9], 0, v[4:5]
	s_load_dwordx2 s[16:17], s[0:1], 0x140
	global_load_dwordx4 v[68:71], v[6:7], off
	global_load_dwordx4 v[72:75], v[6:7], off offset:32
	global_load_dwordx4 v[76:79], v[6:7], off offset:64
	global_load_dwordx4 v[80:83], v[6:7], off offset:96
	v_lshl_add_u64 v[4:5], v[4:5], 0, s[84:85]
	v_lshl_add_u64 v[4:5], v[4:5], 0, v[2:3]
	global_load_dwordx4 v[84:87], v[4:5], off
	global_load_dwordx4 v[88:91], v[4:5], off offset:32
	s_lshl_b32 s8, s14, 22
	s_lshl_b32 s18, s14, 18
	s_lshl_b32 s14, s13, 1
	s_add_u32 s7, s10, s8
	s_addc_u32 s9, s11, 0
	s_add_u32 s6, s7, s6
	s_addc_u32 s7, s9, 0
	s_lshl_b32 s9, s15, 19
	s_or_b32 s8, s8, s9
	v_ashrrev_i32_e32 v134, 3, v22
	v_mov_b32_e32 v4, v3
	s_waitcnt lgkmcnt(0)
	s_add_u32 s8, s16, s8
	v_add_u32_e32 v136, 32, v134
	s_addc_u32 s9, s17, 0
	v_lshlrev_b32_e32 v154, 6, v134
	v_lshlrev_b32_e32 v156, 6, v136
	v_ashrrev_i32_e32 v158, 2, v22
	v_and_b32_e32 v6, 7, v22
	v_lshlrev_b32_e32 v4, 2, v22
	s_add_u32 s4, s4, s18
	v_ashrrev_i32_e32 v137, 31, v136
	v_ashrrev_i32_e32 v155, 31, v154
	v_ashrrev_i32_e32 v157, 31, v156
	v_ashrrev_i32_e32 v159, 31, v158
	v_lshlrev_b32_e32 v132, 3, v6
	v_and_b32_e32 v4, 4, v4
	s_addc_u32 s5, s5, 0
	v_ashrrev_i32_e32 v135, 31, v134
	v_lshlrev_b64 v[8:9], 10, v[136:137]
	v_lshlrev_b64 v[28:29], 1, v[154:155]
	v_lshlrev_b64 v[30:31], 1, v[156:157]
	v_lshlrev_b64 v[20:21], 6, v[158:159]
	v_and_b32_e32 v22, 3, v22
	v_and_or_b32 v38, v132, 48, v4
	v_lshlrev_b64 v[4:5], 10, v[134:135]
	v_lshlrev_b32_e32 v24, 4, v6
	v_mov_b32_e32 v25, v3
	v_lshl_add_u64 v[8:9], s[6:7], 0, v[8:9]
	v_lshl_add_u64 v[12:13], s[8:9], 0, v[28:29]
	v_lshl_add_u64 v[16:17], s[8:9], 0, v[30:31]
	v_lshl_add_u64 v[20:21], s[4:5], 0, v[20:21]
	v_lshlrev_b32_e32 v34, 4, v22
	v_mov_b32_e32 v35, v3
	s_movk_i32 s17, 0xd0
	v_lshl_add_u64 v[4:5], s[6:7], 0, v[4:5]
	v_lshl_add_u64 v[8:9], v[8:9], 0, v[24:25]
	v_lshl_add_u64 v[12:13], v[12:13], 0, v[24:25]
	v_lshl_add_u64 v[16:17], v[16:17], 0, v[24:25]
	v_lshl_add_u64 v[36:37], v[20:21], 0, v[34:35]
	v_mul_lo_u32 v35, v134, s17
	s_barrier
	v_lshl_add_u64 v[26:27], v[4:5], 0, v[24:25]
	global_load_dwordx4 v[4:7], v[26:27], off
	global_load_dwordx4 v[8:11], v[8:9], off
	global_load_dwordx4 v[12:15], v[12:13], off
	global_load_dwordx4 v[16:19], v[16:17], off
	v_lshlrev_b32_e32 v32, 3, v22
	global_load_dwordx4 v[20:23], v[36:37], off
	v_mov_b32_e32 v135, v3
	v_add_u32_e32 v35, s3, v35
	s_mov_b64 s[10:11], 0x10000
	v_lshl_add_u64 v[226:227], v[26:27], 0, s[10:11]
	global_load_dwordx4 v[92:95], v[226:227], off
	s_mov_b64 s[10:11], 0x18000
	v_lshl_add_u64 v[226:227], v[26:27], 0, s[10:11]
	global_load_dwordx4 v[96:99], v[226:227], off
	s_add_u32 s10, s8, 0x2000
	s_addc_u32 s11, s9, 0
	v_lshl_add_u64 v[226:227], s[10:11], 0, v[28:29]
	v_lshl_add_u64 v[226:227], v[226:227], 0, v[24:25]
	global_load_dwordx4 v[100:103], v[226:227], off
	v_lshl_add_u64 v[226:227], s[10:11], 0, v[30:31]
	v_lshl_add_u64 v[226:227], v[226:227], 0, v[24:25]
	global_load_dwordx4 v[104:107], v[226:227], off
	v_lshl_add_u64 v[226:227], v[36:37], 0, s[38:39]
	global_load_dwordx4 v[108:111], v[226:227], off
	s_waitcnt vmcnt(5)
	v_add_u32_e32 v137, v35, v24
	ds_write_b128 v137, v[4:7]
	v_add_u32_e32 v4, 0x1a00, v35
	v_add_u32_e32 v159, v4, v24
	v_mul_lo_u32 v4, v134, s74
	v_add_u32_e32 v4, s3, v4
	v_lshlrev_b32_e32 v5, 1, v38
	v_add_u32_e32 v177, v4, v5
	v_add_u32_e32 v4, 0x1200, v4
	v_add_u32_e32 v179, v4, v5
	v_mul_lo_u32 v4, v158, s17
	v_add_u32_e32 v4, s3, v4
	s_add_i32 s15, s14, 2
	s_or_b32 s16, s14, 1
	v_add_u32_e32 v178, 0x3000, v177
	v_add_u32_e32 v180, 0x3000, v179
	v_add_u32_e32 v181, v4, v34
	ds_write_b128 v159, v[8:11]
	ds_write2_b64 v178, v[12:13], v[14:15] offset0:128 offset1:130
	ds_write2_b64 v180, v[16:17], v[18:19] offset0:128 offset1:130
	ds_write_b128 v181, v[20:23] offset:128
	v_mov_b32_e32 v4, s3
	v_mad_u32_u24 v20, v33, s17, v4
	v_mad_u32_u24 v21, v33, s74, v4
	v_mov_b32_e32 v18, v3
	v_mov_b32_e32 v19, v3
	v_mov_b32_e32 v4, v3
	v_mov_b32_e32 v5, v3
	v_mov_b32_e32 v6, v3
	v_mov_b32_e32 v7, v3
	v_mov_b32_e32 v8, v3
	v_mov_b32_e32 v9, v3
	v_mov_b32_e32 v10, v3
	v_mov_b32_e32 v11, v3
	v_mov_b32_e32 v12, v3
	v_mov_b32_e32 v13, v3
	v_mov_b32_e32 v14, v3
	v_mov_b32_e32 v15, v3
	v_mov_b32_e32 v16, v3
	v_mov_b32_e32 v17, v3
	v_lshlrev_b32_e32 v160, 1, v32
	v_add_u32_e32 v183, v20, v2
	v_add_u32_e32 v184, v21, v2
	v_mov_b64_e32 v[34:35], v[18:19]
	s_mov_b32 s12, 3
	v_mov_b32_e32 v163, 0xf149f2ca
	v_mov_b32_e32 v182, 0
	s_mov_b32 s17, 64
	v_mov_b64_e32 v[32:33], v[16:17]
	v_mov_b64_e32 v[30:31], v[14:15]
	v_mov_b64_e32 v[28:29], v[12:13]
	v_mov_b64_e32 v[26:27], v[10:11]
	v_mov_b64_e32 v[24:25], v[8:9]
	v_mov_b64_e32 v[22:23], v[6:7]
	v_mov_b64_e32 v[20:21], v[4:5]
	v_mov_b32_e32 v185, 0
	s_waitcnt lgkmcnt(0)
	s_barrier
	s_cmp_eq_u32 s3, 0
	s_cbranch_scc1 .Lmla_nostag_in
	s_barrier
